# adds: memory cross-attention block epilogue also LDS-transposed to 4 x dwordx4 full-row stores (was 32 ds_swizzle + 32 dword stores per wave)
# baseline (speedup 1.0000x reference)
.LBB0_416:
	s_and_saveexec_b64 s[26:27], s[38:39]
	ds_write_b32 v134, v48
	s_or_b64 exec, exec, s[26:27]
	s_waitcnt lgkmcnt(0)
	ds_read_b128 v[44:47], v113
	ds_read_b128 v[40:43], v113 offset:32
	ds_read_b128 v[36:39], v113 offset:64
	ds_read_b128 v[32:35], v113 offset:96
	s_lshl_b64 s[20:21], s[20:21], 19
	s_add_u32 s20, s22, s20
	s_addc_u32 s21, s23, s21
	s_lshl_b32 s22, s44, 1
	s_add_u32 s22, s20, s22
	s_addc_u32 s23, s21, 0
	s_ashr_i32 s25, s24, 31
	s_lshl_b64 s[20:21], s[24:25], 11
	s_add_u32 s20, s22, s20
	s_addc_u32 s21, s23, s21
	s_add_u32 s20, s20, 0x2a800600
	s_addc_u32 s21, s21, 0
	v_readlane_b32 s22, v254, 50
	v_lshrrev_b32_e32 v82, 3, v252
	v_and_b32_e32 v83, 7, v252
	s_mul_i32 s22, s22, 0x1800
	s_add_i32 s22, s22, 0xc000
	v_lshlrev_b32_e32 v84, 11, v82
	v_lshl_or_b32 v84, v83, 4, v84
	v_add_u32_e32 v85, 0x4000, v84
	v_add_u32_e32 v86, 0x8000, v84
	v_add_u32_e32 v87, 0xc000, v84
	v_mul_u32_u24_e32 v88, 144, v82
	v_lshl_add_u32 v88, v83, 4, v88
	v_add_u32_e32 v88, s22, v88
	v_lshrrev_b32_e32 v82, 5, v252
	v_and_b32_e32 v83, 31, v252
	v_mul_u32_u24_e32 v89, 576, v82
	v_lshl_add_u32 v89, v83, 1, v89
	v_add_u32_e32 v89, s22, v89
	s_waitcnt lgkmcnt(0)
	v_rcp_f32_e32 v32, v32
	v_rcp_f32_e32 v33, v33
	v_rcp_f32_e32 v34, v34
	v_rcp_f32_e32 v35, v35
	v_rcp_f32_e32 v36, v36
	v_rcp_f32_e32 v37, v37
	v_rcp_f32_e32 v38, v38
	v_rcp_f32_e32 v39, v39
	v_rcp_f32_e32 v40, v40
	v_rcp_f32_e32 v41, v41
	v_rcp_f32_e32 v42, v42
	v_rcp_f32_e32 v43, v43
	v_rcp_f32_e32 v44, v44
	v_rcp_f32_e32 v45, v45
	v_rcp_f32_e32 v46, v46
	v_rcp_f32_e32 v47, v47
	s_nop 0
	v_pk_mul_f32 v[0:1], v[0:1], v[44:45]
	v_pk_mul_f32 v[2:3], v[2:3], v[46:47]
	v_pk_mul_f32 v[4:5], v[4:5], v[40:41]
	v_pk_mul_f32 v[6:7], v[6:7], v[42:43]
	v_pk_mul_f32 v[8:9], v[8:9], v[36:37]
	v_pk_mul_f32 v[10:11], v[10:11], v[38:39]
	v_pk_mul_f32 v[12:13], v[12:13], v[32:33]
	v_pk_mul_f32 v[14:15], v[14:15], v[34:35]
	v_pk_mul_f32 v[16:17], v[16:17], v[44:45]
	v_pk_mul_f32 v[18:19], v[18:19], v[46:47]
	v_pk_mul_f32 v[20:21], v[20:21], v[40:41]
	v_pk_mul_f32 v[22:23], v[22:23], v[42:43]
	v_pk_mul_f32 v[24:25], v[24:25], v[36:37]
	v_pk_mul_f32 v[26:27], v[26:27], v[38:39]
	v_pk_mul_f32 v[28:29], v[28:29], v[32:33]
	v_pk_mul_f32 v[30:31], v[30:31], v[34:35]
	v_cvt_pk_bf16_f32 v0, v0, v1
	v_cvt_pk_bf16_f32 v2, v2, v3
	v_cvt_pk_bf16_f32 v4, v4, v5
	v_cvt_pk_bf16_f32 v6, v6, v7
	v_cvt_pk_bf16_f32 v8, v8, v9
	v_cvt_pk_bf16_f32 v10, v10, v11
	v_cvt_pk_bf16_f32 v12, v12, v13
	v_cvt_pk_bf16_f32 v14, v14, v15
	v_cvt_pk_bf16_f32 v16, v16, v17
	v_cvt_pk_bf16_f32 v18, v18, v19
	v_cvt_pk_bf16_f32 v20, v20, v21
	v_cvt_pk_bf16_f32 v22, v22, v23
	v_cvt_pk_bf16_f32 v24, v24, v25
	v_cvt_pk_bf16_f32 v26, v26, v27
	v_cvt_pk_bf16_f32 v28, v28, v29
	v_cvt_pk_bf16_f32 v30, v30, v31
	ds_write_b16 v89, v0 offset:0
	ds_write_b16_d16_hi v89, v0 offset:144
	ds_write_b16 v89, v2 offset:288
	ds_write_b16_d16_hi v89, v2 offset:432
	ds_write_b16 v89, v4 offset:1152
	ds_write_b16_d16_hi v89, v4 offset:1296
	ds_write_b16 v89, v6 offset:1440
	ds_write_b16_d16_hi v89, v6 offset:1584
	ds_write_b16 v89, v8 offset:2304
	ds_write_b16_d16_hi v89, v8 offset:2448
	ds_write_b16 v89, v10 offset:2592
	ds_write_b16_d16_hi v89, v10 offset:2736
	ds_write_b16 v89, v12 offset:3456
	ds_write_b16_d16_hi v89, v12 offset:3600
	ds_write_b16 v89, v14 offset:3744
	ds_write_b16_d16_hi v89, v14 offset:3888
	ds_write_b16 v89, v16 offset:64
	ds_write_b16_d16_hi v89, v16 offset:208
	ds_write_b16 v89, v18 offset:352
	ds_write_b16_d16_hi v89, v18 offset:496
	ds_write_b16 v89, v20 offset:1216
	ds_write_b16_d16_hi v89, v20 offset:1360
	ds_write_b16 v89, v22 offset:1504
	ds_write_b16_d16_hi v89, v22 offset:1648
	ds_write_b16 v89, v24 offset:2368
	ds_write_b16_d16_hi v89, v24 offset:2512
	ds_write_b16 v89, v26 offset:2656
	ds_write_b16_d16_hi v89, v26 offset:2800
	ds_write_b16 v89, v28 offset:3520
	ds_write_b16_d16_hi v89, v28 offset:3664
	ds_write_b16 v89, v30 offset:3808
	ds_write_b16_d16_hi v89, v30 offset:3952
	ds_read_b128 v[64:67], v88 offset:0
	ds_read_b128 v[68:71], v88 offset:1152
	ds_read_b128 v[72:75], v88 offset:2304
	ds_read_b128 v[76:79], v88 offset:3456
	s_waitcnt lgkmcnt(3)
	global_store_dwordx4 v84, v[64:67], s[20:21]
	s_waitcnt lgkmcnt(2)
	global_store_dwordx4 v85, v[68:71], s[20:21]
	s_waitcnt lgkmcnt(1)
	global_store_dwordx4 v86, v[72:75], s[20:21]
	s_waitcnt lgkmcnt(0)
	global_store_dwordx4 v87, v[76:79], s[20:21]
	s_branch .LBB0_397
